# v81 + split-phase entry grid sync: arrive at entry, poll only before the first xcd barrier (P0 overlaps the sync)
# speedup vs baseline: 1.0405x; 1.0028x over previous
; #define LAS __attribute__((address_space(3)))
; __global__ void __launch_bounds__(NTHR, 2) fwd_kernel(Args a) {
;     ...
;     grid.sync();
;     const XcdBarrier xbar = xcd_barrier_post((unsigned*)(a.ws + 16384), (volatile LAS unsigned*)(lds + 131072 + 32));
.LBB0_12:
	s_or_b64 exec, exec, s[6:7]
	v_and_b32_e32 v1, 0xffff0000, v1
	s_nop 1
	v_readfirstlane_b32 s6, v1
	s_nop 3
	v_writelane_b32 v255, s6, 40
	v_writelane_b32 v255, s4, 41
	v_writelane_b32 v255, s5, 42

; __device__ __forceinline__ unsigned xb_ld(unsigned* p)              { return __hip_atomic_load(p, __ATOMIC_RELAXED, __HIP_MEMORY_SCOPE_AGENT); }
; __device__ __forceinline__ void xcd_barrier_complete(unsigned* bar, unsigned x, unsigned& nloc, unsigned& nx) {
;     const unsigned G = gridDim.x * gridDim.y * gridDim.z;
;     unsigned sum, cnt, mine, sp = 0u;
;     for (;;) {
;         sum = 0u; cnt = 0u; mine = 0u;
; #pragma unroll
;         for (unsigned j = 0; j < 16; ++j) { const unsigned c = xb_ld(&bar[XB_XCNT(j)]); sum += c; cnt += (c > 0u) ? 1u : 0u; mine = (j == x) ? c : mine; }
; __device__ __forceinline__ void xcd_barrier(const XcdBarrier& b) {
;     asm volatile("s_waitcnt vmcnt(0)" ::: "memory");
;     __syncthreads();
;     if (threadIdx.x == 0) {
;         unsigned* bar = b.bar;
;         __builtin_amdgcn_s_waitcnt(0);
;         unsigned nloc = b.st[0], nx = b.st[1];
;         if (nloc == 0u) { xcd_barrier_complete(bar, b.x, nloc, nx); b.st[0] = nloc; b.st[1] = nx; }
.LBB0_109:
	s_waitcnt vmcnt(0)
	s_barrier
	s_mov_b64 s[0:1], exec
	v_readlane_b32 s2, v254, 35
	v_readlane_b32 s3, v254, 36
	s_and_b64 s[2:3], s[0:1], s[2:3]
	s_mov_b64 exec, s[2:3]
	s_cbranch_execz .LBB0_161
	v_readlane_b32 s2, v255, 41
	v_readlane_b32 s3, v255, 42
	v_readlane_b32 s100, v255, 40
	v_mov_b32_e32 v0, 0
	s_nop 4
.Lcgw_poll:
	global_load_dword v2, v0, s[2:3] offset:32 sc1
	s_waitcnt vmcnt(0)
	v_and_b32_e32 v2, 0xffff0000, v2
	v_cmp_ne_u32_e32 vcc, s100, v2
	s_cbranch_vccnz .Lcgw_done
	s_sleep 1
	s_branch .Lcgw_poll
.Lcgw_done:
	s_add_i32 s2, 0, 0x20020
	v_mov_b32_e32 v0, s2
	s_waitcnt vmcnt(0) expcnt(0) lgkmcnt(0)
	ds_read_b32 v2, v0
	s_add_i32 s2, 0, 0x20024
	v_mov_b32_e32 v0, s2
	ds_read_b32 v0, v0
	s_waitcnt lgkmcnt(1)
	v_cmp_ne_u32_e32 vcc, 0, v2
	s_cbranch_vccnz .LBB0_125
	v_readlane_b32 s2, v254, 0
	s_mul_i32 s33, s87, s2
	s_add_u32 s2, s66, 0x4200
	s_addc_u32 s3, s67, 0
	s_add_u32 s4, s66, 0x4400
	s_addc_u32 s5, s67, 0
	s_add_u32 s12, s66, 0x4500
	s_addc_u32 s13, s67, 0
	s_add_u32 s14, s66, 0x4600
	s_addc_u32 s15, s67, 0
	s_add_u32 s16, s66, 0x4700
	s_addc_u32 s17, s67, 0
	s_add_u32 s18, s66, 0x4800
	s_addc_u32 s19, s67, 0
	s_add_u32 s20, s66, 0x4900
	s_addc_u32 s21, s67, 0
	s_add_u32 s22, s66, 0x4a00
	s_addc_u32 s23, s67, 0
	s_add_u32 s24, s66, 0x4b00
	s_addc_u32 s25, s67, 0
	s_add_u32 s26, s66, 0x4c00
	s_addc_u32 s27, s67, 0
	s_add_u32 s28, s66, 0x4d00
	s_addc_u32 s29, s67, 0
	s_add_u32 s30, s66, 0x4e00
	s_addc_u32 s31, s67, 0
	s_add_u32 s34, s66, 0x4f00
	s_addc_u32 s35, s67, 0
	s_add_u32 s36, s66, 0x5000
	s_addc_u32 s37, s67, 0
	s_add_u32 s38, s66, 0x5100
	s_addc_u32 s39, s67, 0
	s_add_u32 s40, s66, 0x5200
	s_addc_u32 s41, s67, 0
	s_add_u32 s42, s66, 0x5300
	s_mul_i32 s33, s33, s86
	s_addc_u32 s43, s67, 0
	s_mov_b32 s50, 1
	v_mov_b32_e32 v16, 0
	s_branch .LBB0_113
